# LRU y_b epilogue: gate unpack paired with h pairs (no pairing moves)
# baseline (speedup 1.0000x reference)
; #define LAS __attribute__((address_space(3)))
; __device__ __forceinline__ unsigned pk2(float lo, float hi) { return f2bf(lo) | (f2bf(hi) << 16); }
; __device__ __forceinline__ float bflo(unsigned w) { return __uint_as_float(w << 16); }
; __device__ __forceinline__ float bfhi(unsigned w) { return __uint_as_float(w & 0xffff0000u); }
; __device__ __forceinline__ void mix_phase(LAS unsigned char* lds, const Params& p, const int layer) {
;     ...
;                 for (int m = 0; m < 4; ++m)
; #pragma unroll
;                     for (int jj = 0; jj < 4; ++jj) XC[(m * 16 + fq * 4 + jj) * 132 + cw + fr] = hl[m][jj];
;                 __syncthreads();
;             {
;                 const int row = yrow, c16 = yc16; const size_t r = (size_t)(r0 + row);
;                 const v4u g0 = sgc0, g1 = sgc1;
;                 const f32x4 h0 = *(const LAS f32x4*)(XC + row * 132 + c16), h1 = *(const LAS f32x4*)(XC + row * 132 + c16 + 4),
;                             h2 = *(const LAS f32x4*)(XC + row * 132 + c16 + 8), h3 = *(const LAS f32x4*)(XC + row * 132 + c16 + 12);
;                 v4u o0, o1;
;                 o0.x = pk2(h0[0] * bflo(g0.x), h0[1] * bfhi(g0.x)); o0.y = pk2(h0[2] * bflo(g0.y), h0[3] * bfhi(g0.y)); o0.z = pk2(h1[0] * bflo(g0.z), h1[1] * bfhi(g0.z)); o0.w = pk2(h1[2] * bflo(g0.w), h1[3] * bfhi(g0.w));
;                 o1.x = pk2(h2[0] * bflo(g1.x), h2[1] * bfhi(g1.x)); o1.y = pk2(h2[2] * bflo(g1.y), h2[3] * bfhi(g1.y)); o1.z = pk2(h3[0] * bflo(g1.z), h3[1] * bfhi(g1.z)); o1.w = pk2(h3[2] * bflo(g1.w), h3[3] * bfhi(g1.w));
;                 bf16* yp = (bf16*)(ws + WS_YA) + r * KCAT + PW + c0 + c16;
;                 *(v4u*)yp = o0; *(v4u*)(yp + 8) = o1;
.Lpf_skip:
	v_add_u32_e32 v0, 0x400, v151
	ds_write2_b32 v0, v156, v157 offset0:8 offset1:140
	v_add_u32_e32 v0, 0x2000, v151
	ds_write2_b32 v0, v78, v79 offset0:64 offset1:196
	v_add_u32_e32 v0, 0x2400, v151
	ds_write2_b32 v0, v168, v169 offset0:72 offset1:204
	v_add_u32_e32 v0, 0x4200, v151
	ds_write2_b32 v0, v76, v77 offset1:132
	v_add_u32_e32 v0, 0x4600, v151
	ds_write2_b32 v0, v180, v181 offset0:8 offset1:140
	v_add_u32_e32 v0, 0x6200, v151
	ds_write2_b32 v0, v74, v75 offset0:64 offset1:196
	v_add_u32_e32 v0, 0x6600, v151
	ds_write2_b32 v0, v190, v191 offset0:72 offset1:204
	v_lshlrev_b32_e32 v0, 2, v140
	v_add3_u32 v0, s6, v234, v0
	ds_write2_b32 v151, v80, v81 offset1:132
	s_waitcnt lgkmcnt(0)
	s_barrier
	ds_read_b128 v[74:77], v0
	ds_read_b128 v[78:81], v0 offset:16
	ds_read_b128 v[82:85], v0 offset:32
	ds_read_b128 v[86:89], v0 offset:48
	s_waitcnt lgkmcnt(0)
	v_lshlrev_b32_e32 v90, 16, v70
	v_and_b32_e32 v91, 0xffff0000, v70
	v_pk_mul_f32 v[90:91], v[74:75], v[90:91]
	v_cvt_pk_bf16_f32 v70, v90, v91
	v_lshlrev_b32_e32 v92, 16, v71
	v_and_b32_e32 v93, 0xffff0000, v71
	v_pk_mul_f32 v[92:93], v[76:77], v[92:93]
	v_cvt_pk_bf16_f32 v71, v92, v93
	v_lshlrev_b32_e32 v90, 16, v72
	v_and_b32_e32 v91, 0xffff0000, v72
	v_pk_mul_f32 v[90:91], v[78:79], v[90:91]
	v_cvt_pk_bf16_f32 v72, v90, v91
	v_lshlrev_b32_e32 v92, 16, v73
	v_and_b32_e32 v93, 0xffff0000, v73
	v_pk_mul_f32 v[92:93], v[80:81], v[92:93]
	v_cvt_pk_bf16_f32 v73, v92, v93
	v_lshlrev_b32_e32 v90, 16, v66
	v_and_b32_e32 v91, 0xffff0000, v66
	v_pk_mul_f32 v[90:91], v[82:83], v[90:91]
	v_cvt_pk_bf16_f32 v66, v90, v91
	v_lshlrev_b32_e32 v92, 16, v67
	v_and_b32_e32 v93, 0xffff0000, v67
	v_pk_mul_f32 v[92:93], v[84:85], v[92:93]
	v_cvt_pk_bf16_f32 v67, v92, v93
	v_lshlrev_b32_e32 v90, 16, v68
	v_and_b32_e32 v91, 0xffff0000, v68
	v_pk_mul_f32 v[90:91], v[86:87], v[90:91]
	v_cvt_pk_bf16_f32 v68, v90, v91
	v_lshlrev_b32_e32 v92, 16, v69
	v_and_b32_e32 v93, 0xffff0000, v69
	v_pk_mul_f32 v[92:93], v[88:89], v[92:93]
	v_cvt_pk_bf16_f32 v69, v92, v93
	v_mov_b64_e32 v[74:75], s[36:37]
	s_movk_i32 s0, 0x1800
	v_mad_i64_i32 v[74:75], s[0:1], v240, s0, v[74:75]
	s_mov_b32 s53, s80
	v_lshl_add_u64 v[74:75], v[74:75], 0, s[52:53]
	v_mov_b32_e32 v151, v1
	v_lshl_add_u64 v[74:75], v[74:75], 0, v[150:151]
	s_mov_b64 s[0:1], 0x15304800
	v_lshl_add_u64 v[76:77], v[74:75], 0, s[0:1]
	v_add_co_u32_e32 v74, vcc, 0x15304000, v74
	s_mov_b32 s12, s13
	s_nop 0
	v_addc_co_u32_e32 v75, vcc, 0, v75, vcc
	s_andn2_b64 vcc, exec, s[82:83]
	global_store_dwordx4 v[74:75], v[70:73], off offset:2048
	global_store_dwordx4 v[76:77], v[66:69], off offset:16
	s_cbranch_vccz .LBB0_545
